# phase_prep part 2 (q/k RMS-norm + axial rope) hand-written: all loads of a tile in flight, scalar pointers, DPP rotations
# speedup vs baseline: 1.0113x; 1.0113x over previous
; DI int oidx(int i) { asm volatile("" : "+s"(i)); return i; }
; DN void phase_prep(const Params& p, int l, char* smem) {
;     ...
;     for (int i = tid; i < 8 * 112; i += 256) {
;       const int tk = i / 112, gi = i - tk * 112;
;       const int m = m0 + tk, t = m % TT;
;       const bool da = gi < 64;
;       const int gq = gi - 64;
;       const bool isq = da ? (gi < 32) : (gq < 32);
;       const int col = da ? (1152 + 8 * gi) : (isq ? (2720 + 8 * gq) : (2976 + 8 * (gq - 32)));
;       const int dofs = da ? ((gi & 3) * 8) : ((gq & 7) * 8);
;       bfr* ptr = P + (size_t)m * PW + col;
;       float x[8], gs[8];
;       unpack8(*(const u32x4*)ptr, x);
;       load8f(da ? (p.in[oidx(21)] + (l * 2 + (isq ? 0 : 1)) * 32 + dofs) : (p.in[oidx(27)] + (l * 2 + (isq ? 0 : 1)) * 64 + dofs), gs);
;     ...
;         load8f(rope + t * 96 + (da ? 0 : 32) + idx0, cs);
;         load8f(rope + t * 96 + (da ? 16 : 64) + idx0, sn);
.LBB0_309:
	s_or_b64 exec, exec, s[8:9]
	s_and_saveexec_b64 s[16:17], s[4:5]
	s_cbranch_execz .LBB0_267
	v_readlane_b32 s98, v253, 13
	s_load_dwordx2 s[6:7], s[0:1], 0xa8
	s_load_dwordx2 s[8:9], s[0:1], 0xd8
	s_load_dwordx2 s[10:11], s[0:1], 0x108
	s_mul_i32 s18, s20, 0x1c72
	s_lshr_b32 s18, s18, 21
	s_mul_i32 s18, s18, 0x120
	s_sub_i32 s18, s20, s18
	s_cmpk_ge_i32 s18, 0x100
	s_cselect_b32 s24, 1, 0
	s_lshl_b32 s18, s18, 3
	s_cmp_eq_u32 s24, 1
	s_cselect_b32 s18, 0, s18
	s_mul_i32 s99, s18, 0x180
	s_waitcnt lgkmcnt(0)
	s_add_u32 s10, s10, 0x2abc000
	s_addc_u32 s11, s11, 0
	s_add_u32 s10, s10, s99
	s_addc_u32 s11, s11, 0
	s_mul_i32 s18, s20, 0xcc00
	s_add_u32 s18, s84, s18
	s_addc_u32 s19, s85, 0
	s_lshl_b32 s99, s98, 8
	v_mov_b32_e32 v0, v183
	v_mul_u32_u24_e32 v1, 0x925, v0
	v_lshrrev_b32_e32 v1, 18, v1
	v_mul_u32_u24_e32 v2, 0x70, v1
	v_sub_u32_e32 v2, v0, v2
	v_cmp_gt_u32_e32 vcc, 64, v2
	v_mov_b32_e32 v3, 0x1140
	v_mov_b32_e32 v4, 0x900
	v_cndmask_b32_e32 v3, v3, v4, vcc
	v_lshl_add_u32 v3, v2, 4, v3
	v_mul_u32_u24_e32 v4, 0x1980, v1
	v_add_u32_e32 v154, v3, v4
	global_load_dwordx4 v[40:43], v154, s[18:19]
	v_and_b32_e32 v5, 3, v2
	v_lshlrev_b32_e32 v5, 5, v5
	v_and_b32_e32 v6, 32, v2
	v_lshl_add_u32 v5, v6, 2, v5
	v_add_u32_e32 v5, s99, v5
	v_subrev_u32_e32 v6, 64, v2
	v_and_b32_e32 v7, 7, v6
	v_lshlrev_b32_e32 v7, 5, v7
	v_and_b32_e32 v8, 32, v6
	v_lshl_add_u32 v7, v8, 3, v7
	v_lshl_add_u32 v7, s99, 1, v7
	v_cndmask_b32_e32 v12, v7, v5, vcc
	v_mov_b32_e32 v8, s8
	v_mov_b32_e32 v9, s9
	v_mov_b32_e32 v10, s6
	v_mov_b32_e32 v11, s7
	v_cndmask_b32_e32 v8, v8, v10, vcc
	v_cndmask_b32_e32 v9, v9, v11, vcc
	v_mov_b32_e32 v13, 0
	v_lshl_add_u64 v[8:9], v[8:9], 0, v[12:13]
	global_load_dwordx4 v[120:123], v[8:9], off
	global_load_dwordx4 v[124:127], v[8:9], off offset:16
	v_and_b32_e32 v5, 1, v2
	v_and_b32_e32 v6, 3, v2
	v_cndmask_b32_e32 v5, v6, v5, vcc
	v_lshlrev_b32_e32 v5, 5, v5
	v_mov_b32_e32 v6, 0x80
	v_cndmask_b32_e64 v6, v6, 0, vcc
	v_add_u32_e32 v5, v5, v6
	v_mul_u32_u24_e32 v6, 0x180, v1
	v_add_u32_e32 v5, v5, v6
	v_mov_b32_e32 v6, 0x80
	v_mov_b32_e32 v7, 0x40
	v_cndmask_b32_e32 v6, v6, v7, vcc
	v_add_u32_e32 v6, v5, v6
	global_load_dwordx4 v[56:59], v5, s[10:11]
	global_load_dwordx4 v[60:63], v5, s[10:11] offset:16
	global_load_dwordx4 v[64:67], v6, s[10:11]
	global_load_dwordx4 v[68:71], v6, s[10:11] offset:16
	v_add_u32_e32 v0, 256, v183
	v_mul_u32_u24_e32 v1, 0x925, v0
	v_lshrrev_b32_e32 v1, 18, v1
	v_mul_u32_u24_e32 v2, 0x70, v1
	v_sub_u32_e32 v2, v0, v2
	v_cmp_gt_u32_e32 vcc, 64, v2
	v_mov_b32_e32 v3, 0x1140
	v_mov_b32_e32 v4, 0x900
	v_cndmask_b32_e32 v3, v3, v4, vcc
	v_lshl_add_u32 v3, v2, 4, v3
	v_mul_u32_u24_e32 v4, 0x1980, v1
	v_add_u32_e32 v155, v3, v4
	global_load_dwordx4 v[44:47], v155, s[18:19]
	v_and_b32_e32 v5, 3, v2
	v_lshlrev_b32_e32 v5, 5, v5
	v_and_b32_e32 v6, 32, v2
	v_lshl_add_u32 v5, v6, 2, v5
	v_add_u32_e32 v5, s99, v5
	v_subrev_u32_e32 v6, 64, v2
	v_and_b32_e32 v7, 7, v6
	v_lshlrev_b32_e32 v7, 5, v7
	v_and_b32_e32 v8, 32, v6
	v_lshl_add_u32 v7, v8, 3, v7
	v_lshl_add_u32 v7, s99, 1, v7
	v_cndmask_b32_e32 v12, v7, v5, vcc
	v_mov_b32_e32 v8, s8
	v_mov_b32_e32 v9, s9
	v_mov_b32_e32 v10, s6
	v_mov_b32_e32 v11, s7
	v_cndmask_b32_e32 v8, v8, v10, vcc
	v_cndmask_b32_e32 v9, v9, v11, vcc
	v_mov_b32_e32 v13, 0
	v_lshl_add_u64 v[8:9], v[8:9], 0, v[12:13]
	global_load_dwordx4 v[128:131], v[8:9], off
	global_load_dwordx4 v[132:135], v[8:9], off offset:16
	v_and_b32_e32 v5, 1, v2
	v_and_b32_e32 v6, 3, v2
	v_cndmask_b32_e32 v5, v6, v5, vcc
	v_lshlrev_b32_e32 v5, 5, v5
	v_mov_b32_e32 v6, 0x80
	v_cndmask_b32_e64 v6, v6, 0, vcc
	v_add_u32_e32 v5, v5, v6
	v_mul_u32_u24_e32 v6, 0x180, v1
	v_add_u32_e32 v5, v5, v6
	v_mov_b32_e32 v6, 0x80
	v_mov_b32_e32 v7, 0x40
	v_cndmask_b32_e32 v6, v6, v7, vcc
	v_add_u32_e32 v6, v5, v6
	global_load_dwordx4 v[72:75], v5, s[10:11]
	global_load_dwordx4 v[76:79], v5, s[10:11] offset:16
	global_load_dwordx4 v[80:83], v6, s[10:11]
	global_load_dwordx4 v[84:87], v6, s[10:11] offset:16
	v_add_u32_e32 v0, 512, v183
	v_mul_u32_u24_e32 v1, 0x925, v0
	v_lshrrev_b32_e32 v1, 18, v1
	v_mul_u32_u24_e32 v2, 0x70, v1
	v_sub_u32_e32 v2, v0, v2
	v_cmp_gt_u32_e32 vcc, 64, v2
	v_mov_b32_e32 v3, 0x1140
	v_mov_b32_e32 v4, 0x900
	v_cndmask_b32_e32 v3, v3, v4, vcc
	v_lshl_add_u32 v3, v2, 4, v3
	v_mul_u32_u24_e32 v4, 0x1980, v1
	v_add_u32_e32 v156, v3, v4
	global_load_dwordx4 v[48:51], v156, s[18:19]
	v_and_b32_e32 v5, 3, v2
	v_lshlrev_b32_e32 v5, 5, v5
	v_and_b32_e32 v6, 32, v2
	v_lshl_add_u32 v5, v6, 2, v5
	v_add_u32_e32 v5, s99, v5
	v_subrev_u32_e32 v6, 64, v2
	v_and_b32_e32 v7, 7, v6
	v_lshlrev_b32_e32 v7, 5, v7
	v_and_b32_e32 v8, 32, v6
	v_lshl_add_u32 v7, v8, 3, v7
	v_lshl_add_u32 v7, s99, 1, v7
	v_cndmask_b32_e32 v12, v7, v5, vcc
	v_mov_b32_e32 v8, s8
	v_mov_b32_e32 v9, s9
	v_mov_b32_e32 v10, s6
	v_mov_b32_e32 v11, s7
	v_cndmask_b32_e32 v8, v8, v10, vcc
	v_cndmask_b32_e32 v9, v9, v11, vcc
	v_mov_b32_e32 v13, 0
	v_lshl_add_u64 v[8:9], v[8:9], 0, v[12:13]
	global_load_dwordx4 v[136:139], v[8:9], off
	global_load_dwordx4 v[140:143], v[8:9], off offset:16
	v_and_b32_e32 v5, 1, v2
	v_and_b32_e32 v6, 3, v2
	v_cndmask_b32_e32 v5, v6, v5, vcc
	v_lshlrev_b32_e32 v5, 5, v5
	v_mov_b32_e32 v6, 0x80
	v_cndmask_b32_e64 v6, v6, 0, vcc
	v_add_u32_e32 v5, v5, v6
	v_mul_u32_u24_e32 v6, 0x180, v1
	v_add_u32_e32 v5, v5, v6
	v_mov_b32_e32 v6, 0x80
	v_mov_b32_e32 v7, 0x40
	v_cndmask_b32_e32 v6, v6, v7, vcc
	v_add_u32_e32 v6, v5, v6
	global_load_dwordx4 v[88:91], v5, s[10:11]
	global_load_dwordx4 v[92:95], v5, s[10:11] offset:16
	global_load_dwordx4 v[96:99], v6, s[10:11]
	global_load_dwordx4 v[100:103], v6, s[10:11] offset:16
; DN void phase_prep(const Params& p, int l, char* smem) {
;     ...
;       float ss = 0.f;
; #pragma unroll
;       for (int e = 0; e < 8; ++e) ss += x[e] * x[e];
;       ss += dppf<0xB1>(ss); ss += dppf<0x4E>(ss);
;       const float ss8 = ss + dppf<0x141>(ss);
;       const float rstd = da ? rsqrtf(ss * (1.f / 32.f) + 1e-6f) : rsqrtf(ss8 * (1.f / 64.f) + 1e-6f);
;       float y[8];
; #pragma unroll
;       for (int e = 0; e < 8; ++e) y[e] = x[e] * rstd * gs[e];
;       float yp2[8], yp4[8];
; #pragma unroll
;       for (int e = 0; e < 8; ++e) { yp2[e] = __shfl_xor(y[e], 2); yp4[e] = __shfl_xor(y[e], 4); }
;       if (t < TL) {
;         const int idx0 = da ? ((gi & 1) * 8) : ((gq & 3) * 8);
;         const bool first = da ? ((gi & 2) == 0) : ((gq & 4) == 0);
;         float cs[8], sn[8];
;         load8f(rope + t * 96 + (da ? 0 : 32) + idx0, cs);
;         load8f(rope + t * 96 + (da ? 16 : 64) + idx0, sn);
; #pragma unroll
;         for (int e = 0; e < 8; ++e) {
;           const float yp = da ? yp2[e] : yp4[e];
;           y[e] = first ? (y[e] * cs[e] - yp * sn[e]) : (y[e] * cs[e] + yp * sn[e]);
;         }
;       }
	v_add_u32_e32 v0, 768, v183
	v_mul_u32_u24_e32 v1, 0x925, v0
	v_lshrrev_b32_e32 v1, 18, v1
	v_mul_u32_u24_e32 v2, 0x70, v1
	v_sub_u32_e32 v2, v0, v2
	v_cmp_gt_u32_e32 vcc, 64, v2
	v_mov_b32_e32 v3, 0x1140
	v_mov_b32_e32 v4, 0x900
	v_cndmask_b32_e32 v3, v3, v4, vcc
	v_lshl_add_u32 v3, v2, 4, v3
	v_mul_u32_u24_e32 v4, 0x1980, v1
	v_add_u32_e32 v157, v3, v4
	global_load_dwordx4 v[52:55], v157, s[18:19]
	v_and_b32_e32 v5, 3, v2
	v_lshlrev_b32_e32 v5, 5, v5
	v_and_b32_e32 v6, 32, v2
	v_lshl_add_u32 v5, v6, 2, v5
	v_add_u32_e32 v5, s99, v5
	v_subrev_u32_e32 v6, 64, v2
	v_and_b32_e32 v7, 7, v6
	v_lshlrev_b32_e32 v7, 5, v7
	v_and_b32_e32 v8, 32, v6
	v_lshl_add_u32 v7, v8, 3, v7
	v_lshl_add_u32 v7, s99, 1, v7
	v_cndmask_b32_e32 v12, v7, v5, vcc
	v_mov_b32_e32 v8, s8
	v_mov_b32_e32 v9, s9
	v_mov_b32_e32 v10, s6
	v_mov_b32_e32 v11, s7
	v_cndmask_b32_e32 v8, v8, v10, vcc
	v_cndmask_b32_e32 v9, v9, v11, vcc
	v_mov_b32_e32 v13, 0
	v_lshl_add_u64 v[8:9], v[8:9], 0, v[12:13]
	global_load_dwordx4 v[144:147], v[8:9], off
	global_load_dwordx4 v[148:151], v[8:9], off offset:16
	v_and_b32_e32 v5, 1, v2
	v_and_b32_e32 v6, 3, v2
	v_cndmask_b32_e32 v5, v6, v5, vcc
	v_lshlrev_b32_e32 v5, 5, v5
	v_mov_b32_e32 v6, 0x80
	v_cndmask_b32_e64 v6, v6, 0, vcc
	v_add_u32_e32 v5, v5, v6
	v_mul_u32_u24_e32 v6, 0x180, v1
	v_add_u32_e32 v5, v5, v6
	v_mov_b32_e32 v6, 0x80
	v_mov_b32_e32 v7, 0x40
	v_cndmask_b32_e32 v6, v6, v7, vcc
	v_add_u32_e32 v6, v5, v6
	global_load_dwordx4 v[104:107], v5, s[10:11]
	global_load_dwordx4 v[108:111], v5, s[10:11] offset:16
	global_load_dwordx4 v[112:115], v6, s[10:11]
	global_load_dwordx4 v[116:119], v6, s[10:11] offset:16
	s_waitcnt vmcnt(21)
	v_mov_b32_e32 v0, v183
	v_mul_u32_u24_e32 v1, 0x925, v0
	v_lshrrev_b32_e32 v1, 18, v1
	v_mul_u32_u24_e32 v2, 0x70, v1
	v_sub_u32_e32 v2, v0, v2
	v_cmp_gt_u32_e64 s[6:7], 64, v2
	v_lshlrev_b32_e32 v8, 16, v40
	v_and_b32_e32 v9, 0xffff0000, v40
	v_lshlrev_b32_e32 v10, 16, v41
	v_and_b32_e32 v11, 0xffff0000, v41
	v_lshlrev_b32_e32 v12, 16, v42
	v_and_b32_e32 v13, 0xffff0000, v42
	v_lshlrev_b32_e32 v14, 16, v43
	v_and_b32_e32 v15, 0xffff0000, v43
	v_mul_f32_e32 v16, v8, v8
	v_fmac_f32_e32 v16, v9, v9
	v_fmac_f32_e32 v16, v10, v10
	v_fmac_f32_e32 v16, v11, v11
	v_fmac_f32_e32 v16, v12, v12
	v_fmac_f32_e32 v16, v13, v13
	v_fmac_f32_e32 v16, v14, v14
	v_fmac_f32_e32 v16, v15, v15
	s_nop 1
	v_add_f32_dpp v16, v16, v16 quad_perm:[1,0,3,2] row_mask:0xf bank_mask:0xf bound_ctrl:1
	s_nop 1
	v_add_f32_dpp v16, v16, v16 quad_perm:[2,3,0,1] row_mask:0xf bank_mask:0xf bound_ctrl:1
	s_nop 1
	v_add_f32_dpp v17, v16, v16 row_half_mirror row_mask:0xf bank_mask:0xf bound_ctrl:1
	v_mul_f32_e32 v16, 0x3d000000, v16
	v_mul_f32_e32 v17, 0x3c800000, v17
	v_cndmask_b32_e64 v16, v17, v16, s[6:7]
	v_add_f32_e32 v16, 0x358637bd, v16
	v_rsq_f32_e32 v16, v16
	s_nop 0
	v_mul_f32_e32 v8, v16, v8
	v_mul_f32_e32 v9, v16, v9
	v_mul_f32_e32 v10, v16, v10
	v_mul_f32_e32 v11, v16, v11
	v_mul_f32_e32 v12, v16, v12
	v_mul_f32_e32 v13, v16, v13
	v_mul_f32_e32 v14, v16, v14
	v_mul_f32_e32 v15, v16, v15
	v_mul_f32_e32 v8, v120, v8
	v_mul_f32_e32 v9, v121, v9
	v_mul_f32_e32 v10, v122, v10
	v_mul_f32_e32 v11, v123, v11
	v_mul_f32_e32 v12, v124, v12
	v_mul_f32_e32 v13, v125, v13
	v_mul_f32_e32 v14, v126, v14
	v_mul_f32_e32 v15, v127, v15
	s_cmp_eq_u32 s24, 1
	s_cbranch_scc1 .Lprep_norope_0
	v_and_b32_e32 v3, 2, v2
	v_and_b32_e32 v4, 4, v2
	v_lshlrev_b32_e32 v3, 1, v3
	v_cndmask_b32_e64 v3, v4, v3, s[6:7]
	v_lshlrev_b32_e32 v3, 29, v3
	v_xor_b32_e32 v3, 0x80000000, v3
	v_xor_b32_e32 v64, v3, v64
	v_xor_b32_e32 v65, v3, v65
	v_xor_b32_e32 v66, v3, v66
	v_xor_b32_e32 v67, v3, v67
	v_xor_b32_e32 v68, v3, v68
	v_xor_b32_e32 v69, v3, v69
	v_xor_b32_e32 v70, v3, v70
	v_xor_b32_e32 v71, v3, v71
	v_mul_f32_dpp v17, v8, v64 quad_perm:[2,3,0,1] row_mask:0xf bank_mask:0xf bound_ctrl:1
	v_mul_f32_dpp v18, v9, v65 quad_perm:[2,3,0,1] row_mask:0xf bank_mask:0xf bound_ctrl:1
	v_mul_f32_dpp v19, v10, v66 quad_perm:[2,3,0,1] row_mask:0xf bank_mask:0xf bound_ctrl:1
	v_mul_f32_dpp v20, v11, v67 quad_perm:[2,3,0,1] row_mask:0xf bank_mask:0xf bound_ctrl:1
	v_mul_f32_dpp v21, v12, v68 quad_perm:[2,3,0,1] row_mask:0xf bank_mask:0xf bound_ctrl:1
	v_mul_f32_dpp v22, v13, v69 quad_perm:[2,3,0,1] row_mask:0xf bank_mask:0xf bound_ctrl:1
	v_mul_f32_dpp v23, v14, v70 quad_perm:[2,3,0,1] row_mask:0xf bank_mask:0xf bound_ctrl:1
	v_mul_f32_dpp v24, v15, v71 quad_perm:[2,3,0,1] row_mask:0xf bank_mask:0xf bound_ctrl:1
	v_mul_f32_dpp v32, v8, v64 row_ror:12 row_mask:0xf bank_mask:0x5 bound_ctrl:1
	v_mul_f32_dpp v32, v8, v64 row_ror:4 row_mask:0xf bank_mask:0xa bound_ctrl:1
	v_mul_f32_dpp v33, v9, v65 row_ror:12 row_mask:0xf bank_mask:0x5 bound_ctrl:1
	v_mul_f32_dpp v33, v9, v65 row_ror:4 row_mask:0xf bank_mask:0xa bound_ctrl:1
	v_mul_f32_dpp v34, v10, v66 row_ror:12 row_mask:0xf bank_mask:0x5 bound_ctrl:1
	v_mul_f32_dpp v34, v10, v66 row_ror:4 row_mask:0xf bank_mask:0xa bound_ctrl:1
	v_mul_f32_dpp v35, v11, v67 row_ror:12 row_mask:0xf bank_mask:0x5 bound_ctrl:1
	v_mul_f32_dpp v35, v11, v67 row_ror:4 row_mask:0xf bank_mask:0xa bound_ctrl:1
	v_mul_f32_dpp v36, v12, v68 row_ror:12 row_mask:0xf bank_mask:0x5 bound_ctrl:1
	v_mul_f32_dpp v36, v12, v68 row_ror:4 row_mask:0xf bank_mask:0xa bound_ctrl:1
	v_mul_f32_dpp v37, v13, v69 row_ror:12 row_mask:0xf bank_mask:0x5 bound_ctrl:1
	v_mul_f32_dpp v37, v13, v69 row_ror:4 row_mask:0xf bank_mask:0xa bound_ctrl:1
	v_mul_f32_dpp v38, v14, v70 row_ror:12 row_mask:0xf bank_mask:0x5 bound_ctrl:1
	v_mul_f32_dpp v38, v14, v70 row_ror:4 row_mask:0xf bank_mask:0xa bound_ctrl:1
	v_mul_f32_dpp v39, v15, v71 row_ror:12 row_mask:0xf bank_mask:0x5 bound_ctrl:1
	v_mul_f32_dpp v39, v15, v71 row_ror:4 row_mask:0xf bank_mask:0xa bound_ctrl:1
	v_cndmask_b32_e64 v17, v32, v17, s[6:7]
	v_cndmask_b32_e64 v18, v33, v18, s[6:7]
	v_cndmask_b32_e64 v19, v34, v19, s[6:7]
	v_cndmask_b32_e64 v20, v35, v20, s[6:7]
	v_cndmask_b32_e64 v21, v36, v21, s[6:7]
	v_cndmask_b32_e64 v22, v37, v22, s[6:7]
	v_cndmask_b32_e64 v23, v38, v23, s[6:7]
	v_cndmask_b32_e64 v24, v39, v24, s[6:7]
	v_fma_f32 v8, v8, v56, v17
	v_fma_f32 v9, v9, v57, v18
	v_fma_f32 v10, v10, v58, v19
	v_fma_f32 v11, v11, v59, v20
	v_fma_f32 v12, v12, v60, v21
	v_fma_f32 v13, v13, v61, v22
	v_fma_f32 v14, v14, v62, v23
	v_fma_f32 v15, v15, v63, v24
; DI unsigned pack2(float a, float b) { unsigned r; asm volatile("v_cvt_pk_bf16_f32 %0, %1, %2" : "=v"(r) : "v"(a), "v"(b)); return r; }
; DN void phase_prep(const Params& p, int l, char* smem) {
;     ...
;       float ss = 0.f;
; #pragma unroll
;       for (int e = 0; e < 8; ++e) ss += x[e] * x[e];
;       ss += dppf<0xB1>(ss); ss += dppf<0x4E>(ss);
;       const float ss8 = ss + dppf<0x141>(ss);
;       const float rstd = da ? rsqrtf(ss * (1.f / 32.f) + 1e-6f) : rsqrtf(ss8 * (1.f / 64.f) + 1e-6f);
;       float y[8];
; #pragma unroll
;       for (int e = 0; e < 8; ++e) y[e] = x[e] * rstd * gs[e];
;       float yp2[8], yp4[8];
; #pragma unroll
;       for (int e = 0; e < 8; ++e) { yp2[e] = __shfl_xor(y[e], 2); yp4[e] = __shfl_xor(y[e], 4); }
;       if (t < TL) {
;         const int idx0 = da ? ((gi & 1) * 8) : ((gq & 3) * 8);
;         const bool first = da ? ((gi & 2) == 0) : ((gq & 4) == 0);
;         float cs[8], sn[8];
;         load8f(rope + t * 96 + (da ? 0 : 32) + idx0, cs);
;         load8f(rope + t * 96 + (da ? 16 : 64) + idx0, sn);
; #pragma unroll
;         for (int e = 0; e < 8; ++e) {
;           const float yp = da ? yp2[e] : yp4[e];
;           y[e] = first ? (y[e] * cs[e] - yp * sn[e]) : (y[e] * cs[e] + yp * sn[e]);
;         }
;       }
;       const float qs = isq ? (da ? 0.25503486f : 0.18033688f) : 1.f;
;       u32x4 ow; ow.x = pack2(y[0] * qs, y[1] * qs); ow.y = pack2(y[2] * qs, y[3] * qs); ow.z = pack2(y[4] * qs, y[5] * qs); ow.w = pack2(y[6] * qs, y[7] * qs);
;       *(u32x4*)ptr = ow;
.Lprep_norope_0:
	v_mov_b32_e32 v3, 0x3e38aa3b
	v_mov_b32_e32 v4, 0x3e8293ee
	v_cndmask_b32_e64 v3, v3, v4, s[6:7]
	v_subrev_u32_e32 v4, 64, v2
	v_cndmask_b32_e64 v4, v4, v2, s[6:7]
	v_cmp_gt_u32_e32 vcc, 32, v4
	v_mov_b32_e32 v4, 1.0
	s_nop 0
	v_cndmask_b32_e32 v3, v4, v3, vcc
	v_mul_f32_e32 v8, v8, v3
	v_mul_f32_e32 v9, v9, v3
	v_mul_f32_e32 v10, v10, v3
	v_mul_f32_e32 v11, v11, v3
	v_mul_f32_e32 v12, v12, v3
	v_mul_f32_e32 v13, v13, v3
	v_mul_f32_e32 v14, v14, v3
	v_mul_f32_e32 v15, v15, v3
	v_cvt_pk_bf16_f32 v4, v8, v9
	v_cvt_pk_bf16_f32 v5, v10, v11
	v_cvt_pk_bf16_f32 v6, v12, v13
	v_cvt_pk_bf16_f32 v7, v14, v15
	global_store_dwordx4 v154, v[4:7], s[18:19]
	s_nop 1
	s_waitcnt vmcnt(15)
	v_add_u32_e32 v0, 256, v183
	v_mul_u32_u24_e32 v1, 0x925, v0
	v_lshrrev_b32_e32 v1, 18, v1
	v_mul_u32_u24_e32 v2, 0x70, v1
	v_sub_u32_e32 v2, v0, v2
	v_cmp_gt_u32_e64 s[6:7], 64, v2
	v_lshlrev_b32_e32 v8, 16, v44
	v_and_b32_e32 v9, 0xffff0000, v44
	v_lshlrev_b32_e32 v10, 16, v45
	v_and_b32_e32 v11, 0xffff0000, v45
	v_lshlrev_b32_e32 v12, 16, v46
	v_and_b32_e32 v13, 0xffff0000, v46
	v_lshlrev_b32_e32 v14, 16, v47
	v_and_b32_e32 v15, 0xffff0000, v47
	v_mul_f32_e32 v16, v8, v8
	v_fmac_f32_e32 v16, v9, v9
	v_fmac_f32_e32 v16, v10, v10
	v_fmac_f32_e32 v16, v11, v11
	v_fmac_f32_e32 v16, v12, v12
	v_fmac_f32_e32 v16, v13, v13
	v_fmac_f32_e32 v16, v14, v14
	v_fmac_f32_e32 v16, v15, v15
	s_nop 1
	v_add_f32_dpp v16, v16, v16 quad_perm:[1,0,3,2] row_mask:0xf bank_mask:0xf bound_ctrl:1
	s_nop 1
	v_add_f32_dpp v16, v16, v16 quad_perm:[2,3,0,1] row_mask:0xf bank_mask:0xf bound_ctrl:1
	s_nop 1
	v_add_f32_dpp v17, v16, v16 row_half_mirror row_mask:0xf bank_mask:0xf bound_ctrl:1
	v_mul_f32_e32 v16, 0x3d000000, v16
	v_mul_f32_e32 v17, 0x3c800000, v17
	v_cndmask_b32_e64 v16, v17, v16, s[6:7]
	v_add_f32_e32 v16, 0x358637bd, v16
	v_rsq_f32_e32 v16, v16
	s_nop 0
	v_mul_f32_e32 v8, v16, v8
	v_mul_f32_e32 v9, v16, v9
	v_mul_f32_e32 v10, v16, v10
	v_mul_f32_e32 v11, v16, v11
	v_mul_f32_e32 v12, v16, v12
	v_mul_f32_e32 v13, v16, v13
	v_mul_f32_e32 v14, v16, v14
	v_mul_f32_e32 v15, v16, v15
	v_mul_f32_e32 v8, v128, v8
	v_mul_f32_e32 v9, v129, v9
	v_mul_f32_e32 v10, v130, v10
	v_mul_f32_e32 v11, v131, v11
	v_mul_f32_e32 v12, v132, v12
	v_mul_f32_e32 v13, v133, v13
	v_mul_f32_e32 v14, v134, v14
	v_mul_f32_e32 v15, v135, v15
	s_cmp_eq_u32 s24, 1
	s_cbranch_scc1 .Lprep_norope_1
	v_and_b32_e32 v3, 2, v2
	v_and_b32_e32 v4, 4, v2
	v_lshlrev_b32_e32 v3, 1, v3
	v_cndmask_b32_e64 v3, v4, v3, s[6:7]
	v_lshlrev_b32_e32 v3, 29, v3
	v_xor_b32_e32 v3, 0x80000000, v3
	v_xor_b32_e32 v80, v3, v80
	v_xor_b32_e32 v81, v3, v81
	v_xor_b32_e32 v82, v3, v82
	v_xor_b32_e32 v83, v3, v83
	v_xor_b32_e32 v84, v3, v84
	v_xor_b32_e32 v85, v3, v85
	v_xor_b32_e32 v86, v3, v86
	v_xor_b32_e32 v87, v3, v87
	v_mul_f32_dpp v17, v8, v80 quad_perm:[2,3,0,1] row_mask:0xf bank_mask:0xf bound_ctrl:1
	v_mul_f32_dpp v18, v9, v81 quad_perm:[2,3,0,1] row_mask:0xf bank_mask:0xf bound_ctrl:1
	v_mul_f32_dpp v19, v10, v82 quad_perm:[2,3,0,1] row_mask:0xf bank_mask:0xf bound_ctrl:1
	v_mul_f32_dpp v20, v11, v83 quad_perm:[2,3,0,1] row_mask:0xf bank_mask:0xf bound_ctrl:1
	v_mul_f32_dpp v21, v12, v84 quad_perm:[2,3,0,1] row_mask:0xf bank_mask:0xf bound_ctrl:1
	v_mul_f32_dpp v22, v13, v85 quad_perm:[2,3,0,1] row_mask:0xf bank_mask:0xf bound_ctrl:1
	v_mul_f32_dpp v23, v14, v86 quad_perm:[2,3,0,1] row_mask:0xf bank_mask:0xf bound_ctrl:1
	v_mul_f32_dpp v24, v15, v87 quad_perm:[2,3,0,1] row_mask:0xf bank_mask:0xf bound_ctrl:1
	v_mul_f32_dpp v32, v8, v80 row_ror:12 row_mask:0xf bank_mask:0x5 bound_ctrl:1
	v_mul_f32_dpp v32, v8, v80 row_ror:4 row_mask:0xf bank_mask:0xa bound_ctrl:1
	v_mul_f32_dpp v33, v9, v81 row_ror:12 row_mask:0xf bank_mask:0x5 bound_ctrl:1
	v_mul_f32_dpp v33, v9, v81 row_ror:4 row_mask:0xf bank_mask:0xa bound_ctrl:1
	v_mul_f32_dpp v34, v10, v82 row_ror:12 row_mask:0xf bank_mask:0x5 bound_ctrl:1
	v_mul_f32_dpp v34, v10, v82 row_ror:4 row_mask:0xf bank_mask:0xa bound_ctrl:1
	v_mul_f32_dpp v35, v11, v83 row_ror:12 row_mask:0xf bank_mask:0x5 bound_ctrl:1
	v_mul_f32_dpp v35, v11, v83 row_ror:4 row_mask:0xf bank_mask:0xa bound_ctrl:1
	v_mul_f32_dpp v36, v12, v84 row_ror:12 row_mask:0xf bank_mask:0x5 bound_ctrl:1
	v_mul_f32_dpp v36, v12, v84 row_ror:4 row_mask:0xf bank_mask:0xa bound_ctrl:1
	v_mul_f32_dpp v37, v13, v85 row_ror:12 row_mask:0xf bank_mask:0x5 bound_ctrl:1
	v_mul_f32_dpp v37, v13, v85 row_ror:4 row_mask:0xf bank_mask:0xa bound_ctrl:1
	v_mul_f32_dpp v38, v14, v86 row_ror:12 row_mask:0xf bank_mask:0x5 bound_ctrl:1
	v_mul_f32_dpp v38, v14, v86 row_ror:4 row_mask:0xf bank_mask:0xa bound_ctrl:1
	v_mul_f32_dpp v39, v15, v87 row_ror:12 row_mask:0xf bank_mask:0x5 bound_ctrl:1
	v_mul_f32_dpp v39, v15, v87 row_ror:4 row_mask:0xf bank_mask:0xa bound_ctrl:1
	v_cndmask_b32_e64 v17, v32, v17, s[6:7]
	v_cndmask_b32_e64 v18, v33, v18, s[6:7]
	v_cndmask_b32_e64 v19, v34, v19, s[6:7]
	v_cndmask_b32_e64 v20, v35, v20, s[6:7]
	v_cndmask_b32_e64 v21, v36, v21, s[6:7]
	v_cndmask_b32_e64 v22, v37, v22, s[6:7]
	v_cndmask_b32_e64 v23, v38, v23, s[6:7]
	v_cndmask_b32_e64 v24, v39, v24, s[6:7]
	v_fma_f32 v8, v8, v72, v17
	v_fma_f32 v9, v9, v73, v18
	v_fma_f32 v10, v10, v74, v19
	v_fma_f32 v11, v11, v75, v20
	v_fma_f32 v12, v12, v76, v21
	v_fma_f32 v13, v13, v77, v22
	v_fma_f32 v14, v14, v78, v23
	v_fma_f32 v15, v15, v79, v24
; DI int oidx(int i) { asm volatile("" : "+s"(i)); return i; }
; DI unsigned pack2(float a, float b) { unsigned r; asm volatile("v_cvt_pk_bf16_f32 %0, %1, %2" : "=v"(r) : "v"(a), "v"(b)); return r; }
; DN void phase_prep(const Params& p, int l, char* smem) {
;     ...
;     for (int i = tid; i < 8 * 112; i += 256) {
;       const int tk = i / 112, gi = i - tk * 112;
;       const int m = m0 + tk, t = m % TT;
;       const bool da = gi < 64;
;       const int gq = gi - 64;
;       const bool isq = da ? (gi < 32) : (gq < 32);
;       const int col = da ? (1152 + 8 * gi) : (isq ? (2720 + 8 * gq) : (2976 + 8 * (gq - 32)));
;       const int dofs = da ? ((gi & 3) * 8) : ((gq & 7) * 8);
;       bfr* ptr = P + (size_t)m * PW + col;
;       float x[8], gs[8];
;       unpack8(*(const u32x4*)ptr, x);
;       load8f(da ? (p.in[oidx(21)] + (l * 2 + (isq ? 0 : 1)) * 32 + dofs) : (p.in[oidx(27)] + (l * 2 + (isq ? 0 : 1)) * 64 + dofs), gs);
;       float ss = 0.f;
; #pragma unroll
;       for (int e = 0; e < 8; ++e) ss += x[e] * x[e];
;       ss += dppf<0xB1>(ss); ss += dppf<0x4E>(ss);
;       const float ss8 = ss + dppf<0x141>(ss);
;       const float rstd = da ? rsqrtf(ss * (1.f / 32.f) + 1e-6f) : rsqrtf(ss8 * (1.f / 64.f) + 1e-6f);
;       float y[8];
; #pragma unroll
;       for (int e = 0; e < 8; ++e) y[e] = x[e] * rstd * gs[e];
;       float yp2[8], yp4[8];
; #pragma unroll
;       for (int e = 0; e < 8; ++e) { yp2[e] = __shfl_xor(y[e], 2); yp4[e] = __shfl_xor(y[e], 4); }
;       if (t < TL) {
;         const int idx0 = da ? ((gi & 1) * 8) : ((gq & 3) * 8);
;         const bool first = da ? ((gi & 2) == 0) : ((gq & 4) == 0);
;         float cs[8], sn[8];
;         load8f(rope + t * 96 + (da ? 0 : 32) + idx0, cs);
;         load8f(rope + t * 96 + (da ? 16 : 64) + idx0, sn);
; #pragma unroll
;         for (int e = 0; e < 8; ++e) {
;           const float yp = da ? yp2[e] : yp4[e];
;           y[e] = first ? (y[e] * cs[e] - yp * sn[e]) : (y[e] * cs[e] + yp * sn[e]);
;         }
;       }
;       const float qs = isq ? (da ? 0.25503486f : 0.18033688f) : 1.f;
;       u32x4 ow; ow.x = pack2(y[0] * qs, y[1] * qs); ow.y = pack2(y[2] * qs, y[3] * qs); ow.z = pack2(y[4] * qs, y[5] * qs); ow.w = pack2(y[6] * qs, y[7] * qs);
;       *(u32x4*)ptr = ow;
.Lprep_norope_1:
	v_mov_b32_e32 v3, 0x3e38aa3b
	v_mov_b32_e32 v4, 0x3e8293ee
	v_cndmask_b32_e64 v3, v3, v4, s[6:7]
	v_subrev_u32_e32 v4, 64, v2
	v_cndmask_b32_e64 v4, v4, v2, s[6:7]
	v_cmp_gt_u32_e32 vcc, 32, v4
	v_mov_b32_e32 v4, 1.0
	s_nop 0
	v_cndmask_b32_e32 v3, v4, v3, vcc
	v_mul_f32_e32 v8, v8, v3
	v_mul_f32_e32 v9, v9, v3
	v_mul_f32_e32 v10, v10, v3
	v_mul_f32_e32 v11, v11, v3
	v_mul_f32_e32 v12, v12, v3
	v_mul_f32_e32 v13, v13, v3
	v_mul_f32_e32 v14, v14, v3
	v_mul_f32_e32 v15, v15, v3
	v_cvt_pk_bf16_f32 v4, v8, v9
	v_cvt_pk_bf16_f32 v5, v10, v11
	v_cvt_pk_bf16_f32 v6, v12, v13
	v_cvt_pk_bf16_f32 v7, v14, v15
	global_store_dwordx4 v155, v[4:7], s[18:19]
	s_nop 1
	s_waitcnt vmcnt(9)
	v_add_u32_e32 v0, 512, v183
	v_mul_u32_u24_e32 v1, 0x925, v0
	v_lshrrev_b32_e32 v1, 18, v1
	v_mul_u32_u24_e32 v2, 0x70, v1
	v_sub_u32_e32 v2, v0, v2
	v_cmp_gt_u32_e64 s[6:7], 64, v2
	v_lshlrev_b32_e32 v8, 16, v48
	v_and_b32_e32 v9, 0xffff0000, v48
	v_lshlrev_b32_e32 v10, 16, v49
	v_and_b32_e32 v11, 0xffff0000, v49
	v_lshlrev_b32_e32 v12, 16, v50
	v_and_b32_e32 v13, 0xffff0000, v50
	v_lshlrev_b32_e32 v14, 16, v51
	v_and_b32_e32 v15, 0xffff0000, v51
	v_mul_f32_e32 v16, v8, v8
	v_fmac_f32_e32 v16, v9, v9
	v_fmac_f32_e32 v16, v10, v10
	v_fmac_f32_e32 v16, v11, v11
	v_fmac_f32_e32 v16, v12, v12
	v_fmac_f32_e32 v16, v13, v13
	v_fmac_f32_e32 v16, v14, v14
	v_fmac_f32_e32 v16, v15, v15
	s_nop 1
	v_add_f32_dpp v16, v16, v16 quad_perm:[1,0,3,2] row_mask:0xf bank_mask:0xf bound_ctrl:1
	s_nop 1
	v_add_f32_dpp v16, v16, v16 quad_perm:[2,3,0,1] row_mask:0xf bank_mask:0xf bound_ctrl:1
	s_nop 1
	v_add_f32_dpp v17, v16, v16 row_half_mirror row_mask:0xf bank_mask:0xf bound_ctrl:1
	v_mul_f32_e32 v16, 0x3d000000, v16
	v_mul_f32_e32 v17, 0x3c800000, v17
	v_cndmask_b32_e64 v16, v17, v16, s[6:7]
	v_add_f32_e32 v16, 0x358637bd, v16
	v_rsq_f32_e32 v16, v16
	s_nop 0
	v_mul_f32_e32 v8, v16, v8
	v_mul_f32_e32 v9, v16, v9
	v_mul_f32_e32 v10, v16, v10
	v_mul_f32_e32 v11, v16, v11
	v_mul_f32_e32 v12, v16, v12
	v_mul_f32_e32 v13, v16, v13
	v_mul_f32_e32 v14, v16, v14
	v_mul_f32_e32 v15, v16, v15
	v_mul_f32_e32 v8, v136, v8
	v_mul_f32_e32 v9, v137, v9
	v_mul_f32_e32 v10, v138, v10
	v_mul_f32_e32 v11, v139, v11
	v_mul_f32_e32 v12, v140, v12
	v_mul_f32_e32 v13, v141, v13
	v_mul_f32_e32 v14, v142, v14
	v_mul_f32_e32 v15, v143, v15
	s_cmp_eq_u32 s24, 1
	s_cbranch_scc1 .Lprep_norope_2
	v_and_b32_e32 v3, 2, v2
	v_and_b32_e32 v4, 4, v2
	v_lshlrev_b32_e32 v3, 1, v3
	v_cndmask_b32_e64 v3, v4, v3, s[6:7]
	v_lshlrev_b32_e32 v3, 29, v3
	v_xor_b32_e32 v3, 0x80000000, v3
	v_xor_b32_e32 v96, v3, v96
	v_xor_b32_e32 v97, v3, v97
	v_xor_b32_e32 v98, v3, v98
	v_xor_b32_e32 v99, v3, v99
	v_xor_b32_e32 v100, v3, v100
	v_xor_b32_e32 v101, v3, v101
	v_xor_b32_e32 v102, v3, v102
	v_xor_b32_e32 v103, v3, v103
	v_mul_f32_dpp v17, v8, v96 quad_perm:[2,3,0,1] row_mask:0xf bank_mask:0xf bound_ctrl:1
	v_mul_f32_dpp v18, v9, v97 quad_perm:[2,3,0,1] row_mask:0xf bank_mask:0xf bound_ctrl:1
	v_mul_f32_dpp v19, v10, v98 quad_perm:[2,3,0,1] row_mask:0xf bank_mask:0xf bound_ctrl:1
	v_mul_f32_dpp v20, v11, v99 quad_perm:[2,3,0,1] row_mask:0xf bank_mask:0xf bound_ctrl:1
	v_mul_f32_dpp v21, v12, v100 quad_perm:[2,3,0,1] row_mask:0xf bank_mask:0xf bound_ctrl:1
	v_mul_f32_dpp v22, v13, v101 quad_perm:[2,3,0,1] row_mask:0xf bank_mask:0xf bound_ctrl:1
	v_mul_f32_dpp v23, v14, v102 quad_perm:[2,3,0,1] row_mask:0xf bank_mask:0xf bound_ctrl:1
	v_mul_f32_dpp v24, v15, v103 quad_perm:[2,3,0,1] row_mask:0xf bank_mask:0xf bound_ctrl:1
	v_mul_f32_dpp v32, v8, v96 row_ror:12 row_mask:0xf bank_mask:0x5 bound_ctrl:1
	v_mul_f32_dpp v32, v8, v96 row_ror:4 row_mask:0xf bank_mask:0xa bound_ctrl:1
	v_mul_f32_dpp v33, v9, v97 row_ror:12 row_mask:0xf bank_mask:0x5 bound_ctrl:1
	v_mul_f32_dpp v33, v9, v97 row_ror:4 row_mask:0xf bank_mask:0xa bound_ctrl:1
	v_mul_f32_dpp v34, v10, v98 row_ror:12 row_mask:0xf bank_mask:0x5 bound_ctrl:1
	v_mul_f32_dpp v34, v10, v98 row_ror:4 row_mask:0xf bank_mask:0xa bound_ctrl:1
	v_mul_f32_dpp v35, v11, v99 row_ror:12 row_mask:0xf bank_mask:0x5 bound_ctrl:1
	v_mul_f32_dpp v35, v11, v99 row_ror:4 row_mask:0xf bank_mask:0xa bound_ctrl:1
	v_mul_f32_dpp v36, v12, v100 row_ror:12 row_mask:0xf bank_mask:0x5 bound_ctrl:1
	v_mul_f32_dpp v36, v12, v100 row_ror:4 row_mask:0xf bank_mask:0xa bound_ctrl:1
	v_mul_f32_dpp v37, v13, v101 row_ror:12 row_mask:0xf bank_mask:0x5 bound_ctrl:1
	v_mul_f32_dpp v37, v13, v101 row_ror:4 row_mask:0xf bank_mask:0xa bound_ctrl:1
	v_mul_f32_dpp v38, v14, v102 row_ror:12 row_mask:0xf bank_mask:0x5 bound_ctrl:1
	v_mul_f32_dpp v38, v14, v102 row_ror:4 row_mask:0xf bank_mask:0xa bound_ctrl:1
	v_mul_f32_dpp v39, v15, v103 row_ror:12 row_mask:0xf bank_mask:0x5 bound_ctrl:1
	v_mul_f32_dpp v39, v15, v103 row_ror:4 row_mask:0xf bank_mask:0xa bound_ctrl:1
	v_cndmask_b32_e64 v17, v32, v17, s[6:7]
	v_cndmask_b32_e64 v18, v33, v18, s[6:7]
	v_cndmask_b32_e64 v19, v34, v19, s[6:7]
	v_cndmask_b32_e64 v20, v35, v20, s[6:7]
	v_cndmask_b32_e64 v21, v36, v21, s[6:7]
	v_cndmask_b32_e64 v22, v37, v22, s[6:7]
	v_cndmask_b32_e64 v23, v38, v23, s[6:7]
	v_cndmask_b32_e64 v24, v39, v24, s[6:7]
	v_fma_f32 v8, v8, v88, v17
	v_fma_f32 v9, v9, v89, v18
	v_fma_f32 v10, v10, v90, v19
	v_fma_f32 v11, v11, v91, v20
	v_fma_f32 v12, v12, v92, v21
	v_fma_f32 v13, v13, v93, v22
	v_fma_f32 v14, v14, v94, v23
	v_fma_f32 v15, v15, v95, v24
; DI int oidx(int i) { asm volatile("" : "+s"(i)); return i; }
; DI unsigned pack2(float a, float b) { unsigned r; asm volatile("v_cvt_pk_bf16_f32 %0, %1, %2" : "=v"(r) : "v"(a), "v"(b)); return r; }
; DN void phase_prep(const Params& p, int l, char* smem) {
;     ...
;     for (int i = tid; i < 8 * 112; i += 256) {
;       const int tk = i / 112, gi = i - tk * 112;
;       const int m = m0 + tk, t = m % TT;
;       const bool da = gi < 64;
;       const int gq = gi - 64;
;       const bool isq = da ? (gi < 32) : (gq < 32);
;       const int col = da ? (1152 + 8 * gi) : (isq ? (2720 + 8 * gq) : (2976 + 8 * (gq - 32)));
;       const int dofs = da ? ((gi & 3) * 8) : ((gq & 7) * 8);
;       bfr* ptr = P + (size_t)m * PW + col;
;       float x[8], gs[8];
;       unpack8(*(const u32x4*)ptr, x);
;       load8f(da ? (p.in[oidx(21)] + (l * 2 + (isq ? 0 : 1)) * 32 + dofs) : (p.in[oidx(27)] + (l * 2 + (isq ? 0 : 1)) * 64 + dofs), gs);
;       float ss = 0.f;
; #pragma unroll
;       for (int e = 0; e < 8; ++e) ss += x[e] * x[e];
;       ss += dppf<0xB1>(ss); ss += dppf<0x4E>(ss);
;       const float ss8 = ss + dppf<0x141>(ss);
;       const float rstd = da ? rsqrtf(ss * (1.f / 32.f) + 1e-6f) : rsqrtf(ss8 * (1.f / 64.f) + 1e-6f);
;       float y[8];
; #pragma unroll
;       for (int e = 0; e < 8; ++e) y[e] = x[e] * rstd * gs[e];
;       float yp2[8], yp4[8];
; #pragma unroll
;       for (int e = 0; e < 8; ++e) { yp2[e] = __shfl_xor(y[e], 2); yp4[e] = __shfl_xor(y[e], 4); }
;       if (t < TL) {
;         const int idx0 = da ? ((gi & 1) * 8) : ((gq & 3) * 8);
;         const bool first = da ? ((gi & 2) == 0) : ((gq & 4) == 0);
;         float cs[8], sn[8];
;         load8f(rope + t * 96 + (da ? 0 : 32) + idx0, cs);
;         load8f(rope + t * 96 + (da ? 16 : 64) + idx0, sn);
; #pragma unroll
;         for (int e = 0; e < 8; ++e) {
;           const float yp = da ? yp2[e] : yp4[e];
;           y[e] = first ? (y[e] * cs[e] - yp * sn[e]) : (y[e] * cs[e] + yp * sn[e]);
;         }
;       }
;       const float qs = isq ? (da ? 0.25503486f : 0.18033688f) : 1.f;
;       u32x4 ow; ow.x = pack2(y[0] * qs, y[1] * qs); ow.y = pack2(y[2] * qs, y[3] * qs); ow.z = pack2(y[4] * qs, y[5] * qs); ow.w = pack2(y[6] * qs, y[7] * qs);
;       *(u32x4*)ptr = ow;
.Lprep_norope_2:
	v_mov_b32_e32 v3, 0x3e38aa3b
	v_mov_b32_e32 v4, 0x3e8293ee
	v_cndmask_b32_e64 v3, v3, v4, s[6:7]
	v_subrev_u32_e32 v4, 64, v2
	v_cndmask_b32_e64 v4, v4, v2, s[6:7]
	v_cmp_gt_u32_e32 vcc, 32, v4
	v_mov_b32_e32 v4, 1.0
	s_nop 0
	v_cndmask_b32_e32 v3, v4, v3, vcc
	v_mul_f32_e32 v8, v8, v3
	v_mul_f32_e32 v9, v9, v3
	v_mul_f32_e32 v10, v10, v3
	v_mul_f32_e32 v11, v11, v3
	v_mul_f32_e32 v12, v12, v3
	v_mul_f32_e32 v13, v13, v3
	v_mul_f32_e32 v14, v14, v3
	v_mul_f32_e32 v15, v15, v3
	v_cvt_pk_bf16_f32 v4, v8, v9
	v_cvt_pk_bf16_f32 v5, v10, v11
	v_cvt_pk_bf16_f32 v6, v12, v13
	v_cvt_pk_bf16_f32 v7, v14, v15
	global_store_dwordx4 v156, v[4:7], s[18:19]
	s_nop 1
	s_waitcnt vmcnt(3)
	v_add_u32_e32 v0, 768, v183
	v_mul_u32_u24_e32 v1, 0x925, v0
	v_lshrrev_b32_e32 v1, 18, v1
	v_mul_u32_u24_e32 v2, 0x70, v1
	v_sub_u32_e32 v2, v0, v2
	v_cmp_gt_u32_e64 s[6:7], 64, v2
	v_lshlrev_b32_e32 v8, 16, v52
	v_and_b32_e32 v9, 0xffff0000, v52
	v_lshlrev_b32_e32 v10, 16, v53
	v_and_b32_e32 v11, 0xffff0000, v53
	v_lshlrev_b32_e32 v12, 16, v54
	v_and_b32_e32 v13, 0xffff0000, v54
	v_lshlrev_b32_e32 v14, 16, v55
	v_and_b32_e32 v15, 0xffff0000, v55
	v_mul_f32_e32 v16, v8, v8
	v_fmac_f32_e32 v16, v9, v9
	v_fmac_f32_e32 v16, v10, v10
	v_fmac_f32_e32 v16, v11, v11
	v_fmac_f32_e32 v16, v12, v12
	v_fmac_f32_e32 v16, v13, v13
	v_fmac_f32_e32 v16, v14, v14
	v_fmac_f32_e32 v16, v15, v15
	s_nop 1
	v_add_f32_dpp v16, v16, v16 quad_perm:[1,0,3,2] row_mask:0xf bank_mask:0xf bound_ctrl:1
	s_nop 1
	v_add_f32_dpp v16, v16, v16 quad_perm:[2,3,0,1] row_mask:0xf bank_mask:0xf bound_ctrl:1
	s_nop 1
	v_add_f32_dpp v17, v16, v16 row_half_mirror row_mask:0xf bank_mask:0xf bound_ctrl:1
	v_mul_f32_e32 v16, 0x3d000000, v16
	v_mul_f32_e32 v17, 0x3c800000, v17
	v_cndmask_b32_e64 v16, v17, v16, s[6:7]
	v_add_f32_e32 v16, 0x358637bd, v16
	v_rsq_f32_e32 v16, v16
	s_nop 0
	v_mul_f32_e32 v8, v16, v8
	v_mul_f32_e32 v9, v16, v9
	v_mul_f32_e32 v10, v16, v10
	v_mul_f32_e32 v11, v16, v11
	v_mul_f32_e32 v12, v16, v12
	v_mul_f32_e32 v13, v16, v13
	v_mul_f32_e32 v14, v16, v14
	v_mul_f32_e32 v15, v16, v15
	v_mul_f32_e32 v8, v144, v8
	v_mul_f32_e32 v9, v145, v9
	v_mul_f32_e32 v10, v146, v10
	v_mul_f32_e32 v11, v147, v11
	v_mul_f32_e32 v12, v148, v12
	v_mul_f32_e32 v13, v149, v13
	v_mul_f32_e32 v14, v150, v14
	v_mul_f32_e32 v15, v151, v15
	s_cmp_eq_u32 s24, 1
	s_cbranch_scc1 .Lprep_norope_3
	v_and_b32_e32 v3, 2, v2
	v_and_b32_e32 v4, 4, v2
	v_lshlrev_b32_e32 v3, 1, v3
	v_cndmask_b32_e64 v3, v4, v3, s[6:7]
	v_lshlrev_b32_e32 v3, 29, v3
	v_xor_b32_e32 v3, 0x80000000, v3
	v_xor_b32_e32 v112, v3, v112
	v_xor_b32_e32 v113, v3, v113
	v_xor_b32_e32 v114, v3, v114
	v_xor_b32_e32 v115, v3, v115
	v_xor_b32_e32 v116, v3, v116
	v_xor_b32_e32 v117, v3, v117
	v_xor_b32_e32 v118, v3, v118
	v_xor_b32_e32 v119, v3, v119
	v_mul_f32_dpp v17, v8, v112 quad_perm:[2,3,0,1] row_mask:0xf bank_mask:0xf bound_ctrl:1
	v_mul_f32_dpp v18, v9, v113 quad_perm:[2,3,0,1] row_mask:0xf bank_mask:0xf bound_ctrl:1
	v_mul_f32_dpp v19, v10, v114 quad_perm:[2,3,0,1] row_mask:0xf bank_mask:0xf bound_ctrl:1
	v_mul_f32_dpp v20, v11, v115 quad_perm:[2,3,0,1] row_mask:0xf bank_mask:0xf bound_ctrl:1
	v_mul_f32_dpp v21, v12, v116 quad_perm:[2,3,0,1] row_mask:0xf bank_mask:0xf bound_ctrl:1
	v_mul_f32_dpp v22, v13, v117 quad_perm:[2,3,0,1] row_mask:0xf bank_mask:0xf bound_ctrl:1
	v_mul_f32_dpp v23, v14, v118 quad_perm:[2,3,0,1] row_mask:0xf bank_mask:0xf bound_ctrl:1
	v_mul_f32_dpp v24, v15, v119 quad_perm:[2,3,0,1] row_mask:0xf bank_mask:0xf bound_ctrl:1
	v_mul_f32_dpp v32, v8, v112 row_ror:12 row_mask:0xf bank_mask:0x5 bound_ctrl:1
	v_mul_f32_dpp v32, v8, v112 row_ror:4 row_mask:0xf bank_mask:0xa bound_ctrl:1
	v_mul_f32_dpp v33, v9, v113 row_ror:12 row_mask:0xf bank_mask:0x5 bound_ctrl:1
	v_mul_f32_dpp v33, v9, v113 row_ror:4 row_mask:0xf bank_mask:0xa bound_ctrl:1
	v_mul_f32_dpp v34, v10, v114 row_ror:12 row_mask:0xf bank_mask:0x5 bound_ctrl:1
	v_mul_f32_dpp v34, v10, v114 row_ror:4 row_mask:0xf bank_mask:0xa bound_ctrl:1
	v_mul_f32_dpp v35, v11, v115 row_ror:12 row_mask:0xf bank_mask:0x5 bound_ctrl:1
	v_mul_f32_dpp v35, v11, v115 row_ror:4 row_mask:0xf bank_mask:0xa bound_ctrl:1
	v_mul_f32_dpp v36, v12, v116 row_ror:12 row_mask:0xf bank_mask:0x5 bound_ctrl:1
	v_mul_f32_dpp v36, v12, v116 row_ror:4 row_mask:0xf bank_mask:0xa bound_ctrl:1
	v_mul_f32_dpp v37, v13, v117 row_ror:12 row_mask:0xf bank_mask:0x5 bound_ctrl:1
	v_mul_f32_dpp v37, v13, v117 row_ror:4 row_mask:0xf bank_mask:0xa bound_ctrl:1
	v_mul_f32_dpp v38, v14, v118 row_ror:12 row_mask:0xf bank_mask:0x5 bound_ctrl:1
	v_mul_f32_dpp v38, v14, v118 row_ror:4 row_mask:0xf bank_mask:0xa bound_ctrl:1
	v_mul_f32_dpp v39, v15, v119 row_ror:12 row_mask:0xf bank_mask:0x5 bound_ctrl:1
	v_mul_f32_dpp v39, v15, v119 row_ror:4 row_mask:0xf bank_mask:0xa bound_ctrl:1
	v_cndmask_b32_e64 v17, v32, v17, s[6:7]
	v_cndmask_b32_e64 v18, v33, v18, s[6:7]
	v_cndmask_b32_e64 v19, v34, v19, s[6:7]
	v_cndmask_b32_e64 v20, v35, v20, s[6:7]
	v_cndmask_b32_e64 v21, v36, v21, s[6:7]
	v_cndmask_b32_e64 v22, v37, v22, s[6:7]
	v_cndmask_b32_e64 v23, v38, v23, s[6:7]
	v_cndmask_b32_e64 v24, v39, v24, s[6:7]
	v_fma_f32 v8, v8, v104, v17
	v_fma_f32 v9, v9, v105, v18
	v_fma_f32 v10, v10, v106, v19
	v_fma_f32 v11, v11, v107, v20
	v_fma_f32 v12, v12, v108, v21
	v_fma_f32 v13, v13, v109, v22
	v_fma_f32 v14, v14, v110, v23
	v_fma_f32 v15, v15, v111, v24
.Lprep_norope_3:
	v_mov_b32_e32 v3, 0x3e38aa3b
	v_mov_b32_e32 v4, 0x3e8293ee
	v_cndmask_b32_e64 v3, v3, v4, s[6:7]
	v_subrev_u32_e32 v4, 64, v2
	v_cndmask_b32_e64 v4, v4, v2, s[6:7]
	v_cmp_gt_u32_e32 vcc, 32, v4
	v_mov_b32_e32 v4, 1.0
	s_nop 0
	v_cndmask_b32_e32 v3, v4, v3, vcc
	v_mul_f32_e32 v8, v8, v3
	v_mul_f32_e32 v9, v9, v3
	v_mul_f32_e32 v10, v10, v3
	v_mul_f32_e32 v11, v11, v3
	v_mul_f32_e32 v12, v12, v3
	v_mul_f32_e32 v13, v13, v3
	v_mul_f32_e32 v14, v14, v3
	v_mul_f32_e32 v15, v15, v3
	v_cvt_pk_bf16_f32 v4, v8, v9
	v_cvt_pk_bf16_f32 v5, v10, v11
	v_cvt_pk_bf16_f32 v6, v12, v13
	v_cvt_pk_bf16_f32 v7, v14, v15
	v_cmp_gt_u32_e32 vcc, 0x80, v183
	s_and_saveexec_b64 s[8:9], vcc
	s_nop 1
	global_store_dwordx4 v157, v[4:7], s[18:19]
	s_or_b64 exec, exec, s[8:9]
	s_branch .LBB0_267
